# strategy #4 in the non-GEMM phases: one static s_setprio 1 for waves 4-7 through the dil/retA, retB/combine and swa unit loops (reset at phase exit)
# speedup vs baseline: 1.0033x; 1.0026x over previous
.LBB0_478:
	v_readlane_b32 s4, v254, 9
	s_cmp_lt_i32 s4, 3
	s_cselect_b64 s[2:3], -1, 0
	s_and_b64 s[0:1], s[2:3], s[0:1]
	s_andn2_b64 vcc, exec, s[0:1]
	v_readlane_b32 s5, v254, 10
	v_readlane_b32 s6, v254, 11
	v_readlane_b32 s7, v254, 12
	s_cbranch_vccnz .LBB0_515
	s_cmp_lt_u32 s89, 4
	s_cbranch_scc1 .Lap_p2
	s_setprio 1
.Lap_p2:
	v_writelane_b32 v254, s0, 33
	s_waitcnt lgkmcnt(0)
	s_add_u32 s78, s96, 0x5500000
	s_addc_u32 s79, s97, 0
	v_writelane_b32 v254, s1, 34
	v_writelane_b32 v254, s89, 35
	s_mov_b32 s0, s88
	s_mov_b64 s[20:21], s[90:91]
	v_writelane_b32 v254, s0, 36
	s_cmpk_gt_i32 s88, 0x5ff
	s_nop 0
	v_writelane_b32 v254, s1, 37
	s_cbranch_scc1 .LBB0_511
	s_mov_b64 s[0:1], 0
	v_mov_b32_e32 v0, 0
	v_mov_b32_e32 v8, 0
	v_mov_b32_e32 v9, 0

.LBB0_515:
	s_setprio 0
	s_waitcnt lgkmcnt(0)
	v_readlane_b32 s76, v254, 9
	v_readlane_b32 s77, v254, 10
	s_cmp_gt_i32 s77, 3
	s_cselect_b64 s[2:3], -1, 0
	s_and_b64 s[0:1], s[0:1], s[2:3]
	v_readlane_b32 s78, v254, 11
	s_andn2_b64 vcc, exec, s[0:1]
	v_readlane_b32 s79, v254, 12
	s_cbranch_vccnz .LBB0_565
	s_waitcnt vmcnt(0)
	s_barrier
	s_mov_b64 s[0:1], exec
	v_readlane_b32 s4, v254, 29
	v_readlane_b32 s5, v254, 30
	s_and_b64 s[4:5], s[0:1], s[4:5]
	s_mov_b64 exec, s[4:5]
	s_cbranch_execz .LBB0_564
	s_add_u32 s4, s96, 0x80200
	s_addc_u32 s5, s97, 0
	s_add_i32 s6, 0, 0x20060
	v_mov_b32_e32 v0, s6
	s_waitcnt vmcnt(0) expcnt(0) lgkmcnt(0)
	ds_read_b32 v2, v0
	s_add_i32 s6, 0, 0x20064
	v_mov_b32_e32 v0, s6
	ds_read_b32 v0, v0
	s_waitcnt lgkmcnt(1)
	v_cmp_ne_u32_e32 vcc, 0, v2
	s_cbranch_vccnz .LBB0_532
	s_mul_i32 s33, s91, s90
	v_readlane_b32 s6, v254, 4
	s_mul_i32 s33, s33, s6
	s_add_u32 s6, s96, 0x80400
	s_addc_u32 s7, s97, 0
	s_add_u32 s8, s96, 0x80500
	s_addc_u32 s9, s97, 0
	s_add_u32 s10, s96, 0x80600
	s_addc_u32 s11, s97, 0
	s_add_u32 s12, s96, 0x80700
	s_addc_u32 s13, s97, 0
	s_add_u32 s14, s96, 0x80800
	s_addc_u32 s15, s97, 0
	s_add_u32 s16, s96, 0x80900
	s_addc_u32 s17, s97, 0
	s_add_u32 s18, s96, 0x80a00
	s_addc_u32 s19, s97, 0
	s_add_u32 s20, s96, 0x80b00
	s_addc_u32 s21, s97, 0
	s_add_u32 s22, s96, 0x80c00
	s_addc_u32 s23, s97, 0
	s_add_u32 s24, s96, 0x80d00
	s_addc_u32 s25, s97, 0
	s_add_u32 s26, s96, 0x80e00
	s_addc_u32 s27, s97, 0
	s_add_u32 s28, s96, 0x80f00
	s_addc_u32 s29, s97, 0
	s_add_u32 s30, s96, 0x81000
	s_addc_u32 s31, s97, 0
	s_add_u32 s34, s96, 0x81100
	s_addc_u32 s35, s97, 0
	s_add_u32 s36, s96, 0x81200
	s_addc_u32 s37, s97, 0
	s_add_u32 s38, s96, 0x81300
	s_addc_u32 s39, s97, 0
	s_mov_b32 s46, 1
	v_mov_b32_e32 v16, 0
	s_branch .LBB0_520

.LBB0_567:
	s_xor_b64 s[42:43], s[0:1], -1
	s_lshr_b32 s0, s88, 2
	s_and_b32 s44, s0, 0x3ffffff8
	s_or_b32 s40, s44, s53
	s_lshl_b32 s36, s40, 6
	s_mov_b32 s37, 0
	s_bfe_u32 s52, s88, 0x20003
	s_lshl_b64 s[0:1], s[36:37], 2
	s_add_u32 s0, s96, s0
	s_addc_u32 s1, s97, s1
	s_add_u32 s38, s0, 0x84000
	s_addc_u32 s39, s1, 0
	s_cmp_lt_i32 s76, 4
	s_cselect_b64 s[0:1], -1, 0
	s_and_b64 s[24:25], s[0:1], s[2:3]
	s_andn2_b64 vcc, exec, s[24:25]
	v_lshlrev_b32_e32 v230, 3, v226
	v_lshrrev_b32_e32 v205, 3, v226
	v_and_b32_e32 v228, 31, v226
	v_lshrrev_b32_e32 v229, 5, v227
	v_lshlrev_b32_e32 v192, 4, v226
	s_cbranch_vccnz .LBB0_706
	s_cmp_lt_u32 s89, 4
	s_cbranch_scc1 .Lap_p3
	s_setprio 1
.Lap_p3:
	s_lshl_b32 s0, s88, 1
	s_and_b32 s8, s0, 0x7fffff80
	s_lshl_b32 s9, s52, 5
	s_lshl_b32 s30, s40, 1
	s_and_b32 s5, s30, 30
	s_or_b32 s0, s9, s8
	s_or_b32 s2, s5, s0
	s_add_u32 s26, s96, 0x5500000
	s_addc_u32 s27, s97, 0
	s_lshr_b32 s36, s88, 6
	v_readlane_b32 s3, v254, 5
	s_lshl_b64 s[34:35], s[36:37], 12
	s_lshl_b32 s1, s5, 7
	v_lshrrev_b32_e32 v152, 4, v226
	v_add_u32_e32 v18, 0x200, v226
	v_add_u32_e32 v10, 0x600, v226
	s_lshr_b32 s4, s3, 7
	s_or_b32 s34, s34, s1
	s_lshl_b32 s36, s52, 7
	v_and_b32_e32 v2, 0x78, v230
	s_lshl_b32 s28, s52, 8
	v_lshrrev_b32_e32 v153, 4, v18
	v_or_b32_e32 v154, 64, v152
	v_lshrrev_b32_e32 v122, 4, v10
	s_lshl_b32 s31, s52, 6
	s_lshl_b32 s41, s4, 5
	v_or_b32_e32 v0, s34, v152
	s_movk_i32 s1, 0x1800
	v_mov_b64_e32 v[24:25], s[26:27]
	v_lshlrev_b32_e32 v118, 1, v2
	v_or_b32_e32 v2, s34, v153
	v_or_b32_e32 v8, s34, v154
	v_or_b32_e32 v10, s34, v122
	v_lshrrev_b32_e32 v116, 3, v18
	s_add_u32 s3, s34, s41
	v_mad_u64_u32 v[0:1], s[6:7], v0, s1, v[24:25]
	v_mov_b32_e32 v28, 0x1800
	v_mad_u64_u32 v[2:3], s[6:7], v2, s1, v[24:25]
	v_mad_u64_u32 v[8:9], s[6:7], v8, s1, v[24:25]
	v_mad_u64_u32 v[10:11], s[6:7], v10, s1, v[24:25]
	v_and_b32_e32 v19, 56, v230
	v_or_b32_e32 v16, s34, v205
	v_or_b32_e32 v18, s34, v116
	v_or_b32_e32 v26, s3, v228
	v_mov_b32_e32 v117, 0
	v_mad_u32_u24 v1, s35, v28, v1
	s_mov_b32 s29, s37
	v_mad_u32_u24 v3, s35, v28, v3
	v_mad_u32_u24 v9, s35, v28, v9
	v_mad_u32_u24 v11, s35, v28, v11
	v_mad_u64_u32 v[16:17], s[6:7], v16, s1, v[24:25]
	v_lshlrev_b32_e32 v120, 1, v19
	v_mad_u64_u32 v[18:19], s[6:7], v18, s1, v[24:25]
	s_addc_u32 s10, s35, 0
	v_mad_u64_u32 v[26:27], s[6:7], v26, s1, v[24:25]
	v_lshl_add_u64 v[0:1], v[0:1], 0, s[28:29]
	v_mov_b32_e32 v119, v117
	v_lshl_add_u64 v[2:3], v[2:3], 0, s[28:29]
	v_lshl_add_u64 v[8:9], v[8:9], 0, s[28:29]
	v_lshl_add_u64 v[10:11], v[10:11], 0, s[28:29]
	v_mad_u32_u24 v17, s35, v28, v17
	v_mad_u32_u24 v19, s35, v28, v19
	v_mad_u32_u24 v27, s10, v28, v27
	v_lshrrev_b32_e32 v112, 2, v226
	v_lshl_add_u64 v[0:1], v[0:1], 0, v[118:119]
	v_lshl_add_u64 v[2:3], v[2:3], 0, v[118:119]
	v_lshl_add_u64 v[8:9], v[8:9], 0, v[118:119]
	v_lshl_add_u64 v[10:11], v[10:11], 0, v[118:119]
	v_lshl_add_u64 v[16:17], v[16:17], 0, s[36:37]
	v_mov_b32_e32 v121, v117
	v_lshl_add_u64 v[18:19], v[18:19], 0, s[36:37]
	v_lshl_add_u64 v[26:27], v[26:27], 0, s[36:37]
	v_lshlrev_b32_e32 v126, 4, v229
	v_mov_b32_e32 v127, v117
	v_or_b32_e32 v119, s34, v112
	v_lshl_add_u64 v[16:17], v[16:17], 0, v[120:121]
	v_lshl_add_u64 v[18:19], v[18:19], 0, v[120:121]
	v_lshl_add_u64 v[26:27], v[26:27], 0, v[126:127]
	v_mad_u64_u32 v[24:25], s[6:7], v119, s1, v[24:25]
	global_load_dwordx4 v[4:7], v[0:1], off offset:1024
	s_nop 0
	global_load_dwordx4 v[0:3], v[2:3], off offset:1024
	s_nop 0
	global_load_dwordx4 v[12:15], v[8:9], off offset:1024
	s_nop 0
	global_load_dwordx4 v[8:11], v[10:11], off offset:1024
	s_nop 0
	global_load_dwordx4 v[20:23], v[16:17], off offset:512
	s_nop 0
	global_load_dwordx4 v[16:19], v[18:19], off offset:512
	s_nop 0
	global_load_dwordx4 v[72:75], v[26:27], off
	global_load_dwordx4 v[76:79], v[26:27], off offset:32
	global_load_dwordx4 v[80:83], v[26:27], off offset:64
	global_load_dwordx4 v[84:87], v[26:27], off offset:96
	v_lshlrev_b32_e32 v26, 5, v226
	s_add_u32 s7, s96, 0xe500000
	s_mov_b32 s3, s37
	v_mad_u32_u24 v25, s35, v28, v25
	v_and_b32_e32 v121, 0x60, v26
	s_addc_u32 s10, s97, 0
	s_lshl_b64 s[2:3], s[2:3], 14
	v_lshl_add_u64 v[24:25], v[24:25], 0, s[28:29]
	v_lshlrev_b32_e32 v114, 1, v121
	v_mov_b32_e32 v115, v117
	s_add_u32 s2, s7, s2
	v_lshl_add_u64 v[24:25], v[24:25], 0, v[114:115]
	s_addc_u32 s3, s10, s3
	v_mov_b32_e32 v193, v117
	global_load_dwordx4 v[56:59], v[24:25], off offset:2096
	global_load_dwordx4 v[60:63], v[24:25], off offset:2080
	global_load_dwordx4 v[64:67], v[24:25], off offset:2064
	global_load_dwordx4 v[68:71], v[24:25], off offset:2048
	v_lshl_add_u64 v[24:25], s[2:3], 0, v[192:193]
	v_add_co_u32_e32 v24, vcc, 0x2000, v24
	v_lshlrev_b32_e32 v155, 3, v229
	s_nop 0
	v_addc_co_u32_e32 v25, vcc, 0, v25, vcc
	global_load_dwordx4 v[52:55], v192, s[2:3]
	global_load_dwordx4 v[48:51], v[24:25], off
	v_cvt_f32_ubyte0_e32 v24, s52
	v_sub_f32_e32 v24, 0xc0a00000, v24
	v_exp_f32_e32 v24, v24
	v_mov_b32_e32 v113, v117
	s_movk_i32 s6, 0x2000
	s_cmp_eq_u32 s5, 0
	v_sub_f32_e32 v24, 1.0, v24
	v_log_f32_e32 v151, v24
	v_mov_b32_e32 v128, v117
	v_mov_b32_e32 v129, v117
	v_mov_b32_e32 v130, v117
	v_mul_f32_e32 v24, 0x43000000, v151
	v_exp_f32_e32 v124, v24
	v_mov_b32_e32 v131, v117
	v_mov_b32_e32 v132, v117
	v_mov_b32_e32 v133, v117
	v_mov_b32_e32 v144, v117
	v_mov_b32_e32 v145, v117
	v_mov_b32_e32 v142, v117
	v_mov_b32_e32 v143, v117
	v_mov_b32_e32 v140, v117
	v_mov_b32_e32 v141, v117
	v_mov_b32_e32 v138, v117
	v_mov_b32_e32 v139, v117
	v_mov_b32_e32 v136, v117
	v_mov_b32_e32 v137, v117
	s_cbranch_scc1 .LBB0_585
	s_mov_b32 s1, 0
	s_lshl_b64 s[2:3], s[0:1], 14
	s_add_u32 s2, s7, s2
	s_addc_u32 s3, s10, s3
	v_mov_b32_e32 v125, v124
	v_add_u32_e32 v134, 0x2000, v192
	s_add_i32 s6, s5, -16
	s_cmp_gt_u32 s5, 16
	s_cbranch_scc1 .Llbt1_Llb_iss
	s_cmp_gt_u32 s5, 8
	s_cbranch_scc1 .Llbt2_Llb_iss
	s_cmp_gt_u32 s5, 4
	s_cbranch_scc1 .Llbt3_Llb_iss
	s_cmp_gt_u32 s5, 2
	s_cbranch_scc1 .Llbt4_Llb_iss
	s_cmp_gt_u32 s5, 1
	s_cbranch_scc1 .Llbt5_Llb_iss
	s_branch .Llb_iss_0

.LBB0_588:
	v_add_u32_e32 v113, v161, v159
	v_sub_u32_e32 v115, v159, v89
	v_sub_u32_e32 v124, v159, v88
	v_sub_u32_e32 v138, v159, v91
	v_sub_u32_e32 v139, v159, v90
	v_sub_u32_e32 v140, v159, v93
	v_sub_u32_e32 v141, v159, v92
	v_sub_u32_e32 v142, v159, v95
	v_sub_u32_e32 v143, v159, v94
	v_cvt_f32_u32_e32 v39, v113
	v_cvt_f32_u32_e32 v40, v124
	v_cvt_f32_u32_e32 v41, v115
	v_cvt_f32_u32_e32 v42, v139
	v_cvt_f32_u32_e32 v43, v138
	v_cvt_f32_u32_e32 v44, v141
	v_cvt_f32_u32_e32 v45, v140
	v_cvt_f32_u32_e32 v46, v143
	v_cvt_f32_u32_e32 v47, v142
	ds_read_b128 v[32:35], v162
	ds_read_b128 v[84:87], v162 offset:32
	ds_read_b128 v[102:105], v162 offset:64
	ds_read_b128 v[106:109], v162 offset:96
	v_add_u32_e32 v36, 0xffffdc00, v160
	v_add_u32_e32 v37, 0xfffffc00, v160
	v_add_u32_e32 v38, 0xffffe000, v160
	ds_read_b64_tr_b16 v[120:121], v36
	ds_read_b64_tr_b16 v[122:123], v36 offset:512
	ds_read_b64_tr_b16 v[116:117], v37
	ds_read_b64_tr_b16 v[118:119], v37 offset:512
	s_waitcnt lgkmcnt(0)
	ds_read_b64_tr_b16 v[130:131], v38
	ds_read_b64_tr_b16 v[132:133], v38 offset:512
	ds_read_b64_tr_b16 v[126:127], v160
	ds_read_b64_tr_b16 v[128:129], v160 offset:512
	s_waitcnt lgkmcnt(0)
	v_mul_f32_e32 v154, v151, v39
	v_mul_f32_e32 v155, v151, v40
	v_mul_f32_e32 v163, v151, v41
	v_mul_f32_e32 v164, v151, v42
	v_mul_f32_e32 v165, v151, v43
	v_mul_f32_e32 v166, v151, v44
	v_mul_f32_e32 v167, v151, v45
	v_mul_f32_e32 v168, v151, v46
	v_mul_f32_e32 v169, v151, v47
	s_waitcnt lgkmcnt(3)
	v_mfma_f32_32x32x16_bf16 v[32:47], v[32:35], v[64:67], 0
	v_add_u32_e32 v152, -1, v113
	v_sub_u32_e32 v144, v159, v97
	v_sub_u32_e32 v145, v159, v96
	v_sub_u32_e32 v146, v159, v99
	v_sub_u32_e32 v147, v159, v98
	v_sub_u32_e32 v148, v159, v101
	v_sub_u32_e32 v149, v159, v100
	s_waitcnt lgkmcnt(2)
	v_mfma_f32_32x32x16_bf16 v[32:47], v[84:87], v[68:71], v[32:47]
	v_cvt_f32_u32_e32 v153, v152
	v_cvt_f32_u32_e32 v110, v145
	v_cvt_f32_u32_e32 v111, v144
	v_cvt_f32_u32_e32 v134, v147
	v_cvt_f32_u32_e32 v135, v146
	v_cvt_f32_u32_e32 v136, v149
	v_cvt_f32_u32_e32 v137, v148
	s_waitcnt lgkmcnt(1)
	v_mfma_f32_32x32x16_bf16 v[32:47], v[102:105], v[72:75], v[32:47]
	v_mul_f32_e32 v153, v151, v153
	v_mul_f32_e32 v170, v151, v110
	v_mul_f32_e32 v171, v151, v111
	v_mul_f32_e32 v173, v151, v134
	v_mul_f32_e32 v174, v151, v135
	v_mul_f32_e32 v136, v151, v136
	v_mul_f32_e32 v137, v151, v137
	s_waitcnt lgkmcnt(0)
	v_mfma_f32_32x32x16_bf16 v[32:47], v[106:109], v[76:79], v[32:47]
	v_exp_f32_e32 v154, v154
	v_exp_f32_e32 v110, v155
	v_exp_f32_e32 v111, v163
	v_exp_f32_e32 v84, v164
	v_exp_f32_e32 v85, v165
	v_exp_f32_e32 v86, v166
	v_exp_f32_e32 v87, v167
	v_exp_f32_e32 v153, v153
	v_exp_f32_e32 v134, v168
	v_exp_f32_e32 v135, v169
	v_exp_f32_e32 v102, v170
	v_exp_f32_e32 v103, v171
	v_exp_f32_e32 v104, v173
	v_exp_f32_e32 v105, v174
	v_exp_f32_e32 v136, v136
	v_exp_f32_e32 v137, v137
	v_mul_f32_e32 v106, v154, v32
	v_mul_f32_e32 v107, v153, v33
	v_cmp_lt_i32_e32 vcc, -1, v152
	v_pk_mul_f32 v[32:33], v[110:111], v[34:35]
	v_pk_mul_f32 v[34:35], v[84:85], v[36:37]
	v_pk_mul_f32 v[36:37], v[86:87], v[38:39]
	v_pk_mul_f32 v[38:39], v[134:135], v[40:41]
	v_pk_mul_f32 v[40:41], v[102:103], v[42:43]
	v_pk_mul_f32 v[42:43], v[104:105], v[44:45]
	v_pk_mul_f32 v[44:45], v[136:137], v[46:47]
	v_cmp_lt_i32_e64 s[0:1], -1, v113
	v_cndmask_b32_e32 v47, 0, v107, vcc
	v_cvt_pk_bf16_f32 v33, v32, v33
	v_cmp_lt_i32_e32 vcc, -1, v124
	v_cvt_pk_bf16_f32 v34, v34, v35
	v_cvt_pk_bf16_f32 v35, v36, v37
	v_cndmask_b32_e64 v46, 0, v106, s[0:1]
	v_cmp_lt_i32_e64 s[0:1], -1, v139
	v_cmp_lt_i32_e64 s[4:5], -1, v141
	v_cvt_pk_bf16_f32 v36, v38, v39
	v_cvt_pk_bf16_f32 v37, v40, v41
	v_cvt_pk_bf16_f32 v39, v44, v45
	v_lshrrev_b32_e32 v40, 16, v34
	v_cmp_lt_i32_e64 s[14:15], -1, v138
	v_lshrrev_b32_e32 v41, 16, v35
	v_cmp_lt_i32_e64 s[16:17], -1, v140
	v_cndmask_b32_e32 v45, 0, v33, vcc
	v_lshrrev_b32_e32 v33, 16, v33
	v_cmp_lt_i32_e32 vcc, -1, v115
	v_cndmask_b32_e64 v34, 0, v34, s[0:1]
	v_cndmask_b32_e64 v35, 0, v35, s[4:5]
	v_cndmask_b32_e32 v33, 0, v33, vcc
	v_cndmask_b32_e64 v40, 0, v40, s[14:15]
	v_cndmask_b32_e64 v41, 0, v41, s[16:17]
	v_cvt_pk_bf16_f32 v32, v46, v47
	v_perm_b32 v33, v33, v45, s3
	v_perm_b32 v34, v40, v34, s3
	v_perm_b32 v35, v41, v35, s3
	v_cmp_lt_i32_e64 s[6:7], -1, v143
	v_cvt_pk_bf16_f32 v38, v42, v43
	v_mfma_f32_32x32x16_bf16 v[0:15], v[120:123], v[32:35], v[0:15]
	v_cmp_lt_i32_e64 s[8:9], -1, v145
	v_cmp_lt_i32_e64 s[10:11], -1, v147
	v_cmp_lt_i32_e64 s[12:13], -1, v149
	v_lshrrev_b32_e32 v42, 16, v37
	v_cmp_lt_i32_e64 s[18:19], -1, v144
	v_lshrrev_b32_e32 v43, 16, v38
	v_cmp_lt_i32_e64 s[20:21], -1, v146
	v_mfma_f32_32x32x16_bf16 v[16:31], v[116:119], v[32:35], v[16:31]
	v_lshrrev_b32_e32 v44, 16, v39
	v_cmp_lt_i32_e64 s[22:23], -1, v148
	v_cndmask_b32_e64 v40, 0, v36, s[6:7]
	v_lshrrev_b32_e32 v36, 16, v36
	v_cmp_lt_i32_e32 vcc, -1, v142
	v_cndmask_b32_e64 v37, 0, v37, s[8:9]
	v_cndmask_b32_e64 v38, 0, v38, s[10:11]
	v_cndmask_b32_e64 v39, 0, v39, s[12:13]
	v_cndmask_b32_e32 v36, 0, v36, vcc
	v_cndmask_b32_e64 v33, 0, v42, s[18:19]
	v_cndmask_b32_e64 v34, 0, v43, s[20:21]
	v_cndmask_b32_e64 v35, 0, v44, s[22:23]
	v_perm_b32 v32, v36, v40, s3
	v_perm_b32 v33, v33, v37, s3
	v_perm_b32 v34, v34, v38, s3
	v_perm_b32 v35, v35, v39, s3
	s_add_i32 s2, s2, -1
	v_subrev_u32_e32 v159, 32, v159
	v_mfma_f32_32x32x16_bf16 v[0:15], v[130:133], v[32:35], v[0:15]
	v_add_u32_e32 v162, 0x1200, v162
	s_cmp_lg_u32 s2, 0
	v_add_u32_e32 v160, 0x800, v160
	v_mfma_f32_32x32x16_bf16 v[16:31], v[126:129], v[32:35], v[16:31]
	s_cbranch_scc1 .LBB0_588
	v_lshlrev_b64 v[32:33], 12, v[82:83]
	v_readlane_b32 s4, v254, 0
	v_lshlrev_b32_e32 v36, 11, v82
	v_and_b32_e32 v32, 0xfff00000, v32
	v_readlane_b32 s6, v254, 2
	v_readlane_b32 s7, v254, 3
	s_waitcnt vmcnt(0)
	v_lshlrev_b32_e32 v40, 16, v62
	v_and_b32_e32 v38, 0xffff0000, v62
	v_lshl_add_u64 v[34:35], s[6:7], 0, v[32:33]
	v_and_b32_e32 v32, 0x7f800, v36
	v_mul_f32_e32 v36, 0xbfb8aa3b, v40
	v_mul_f32_e32 v37, 0xbfb8aa3b, v38
	v_exp_f32_e32 v36, v36
	v_exp_f32_e32 v37, v37
	v_mov_b32_e32 v33, 0
	v_lshl_add_u64 v[34:35], v[34:35], 0, v[32:33]
	v_lshlrev_b32_e32 v45, 16, v61
	v_pk_add_f32 v[36:37], v[36:37], 1.0 op_sel_hi:[1,0]
	v_and_b32_e32 v46, 0xffff0000, v61
	v_lshlrev_b32_e32 v66, 16, v63
	v_and_b32_e32 v44, 0xffff0000, v63
	v_lshlrev_b32_e32 v71, 16, v58
	v_rcp_f32_e32 v32, v37
	s_nop 0
	v_mul_f32_e32 v37, v38, v32
	v_mul_f32_e32 v38, 0xbfb8aa3b, v45
	v_mul_f32_e32 v39, 0xbfb8aa3b, v46
	v_exp_f32_e32 v38, v38
	v_exp_f32_e32 v39, v39
	s_nop 0
	v_pk_add_f32 v[38:39], v[38:39], 1.0 op_sel_hi:[1,0]
	v_rcp_f32_e32 v32, v36
	s_nop 0
	v_mul_f32_e32 v36, v40, v32
	v_and_b32_e32 v58, 0xffff0000, v58
	v_rcp_f32_e32 v32, v39
	s_nop 0
	v_mul_f32_e32 v39, v46, v32
	v_lshlrev_b32_e32 v78, 16, v59
	v_lshlrev_b32_e32 v42, 16, v60
	v_and_b32_e32 v43, 0xffff0000, v60
	v_mul_f32_e32 v40, 0xbfb8aa3b, v42
	v_mul_f32_e32 v41, 0xbfb8aa3b, v43
	v_exp_f32_e32 v40, v40
	v_exp_f32_e32 v41, v41
	v_rcp_f32_e32 v32, v38
	s_nop 0
	v_mul_f32_e32 v38, v45, v32
	v_and_b32_e32 v76, 0xffff0000, v59
	v_lshlrev_b32_e32 v77, 16, v57
	v_pk_add_f32 v[40:41], v[40:41], 1.0 op_sel_hi:[1,0]
	v_and_b32_e32 v57, 0xffff0000, v57
	v_div_scale_f32 v67, s[0:1], v41, v41, v43
	v_rcp_f32_e32 v68, v67
	s_waitcnt lgkmcnt(0)
	s_barrier
	v_rcp_f32_e32 v45, v41
	s_nop 0
	v_mul_f32_e32 v41, v43, v45
	ds_write2_b32 v172, v0, v1 offset1:1
	ds_write2_b32 v172, v2, v3 offset0:2 offset1:3
	ds_write2_b32 v172, v4, v5 offset0:8 offset1:9
	ds_write2_b32 v172, v6, v7 offset0:10 offset1:11
	ds_write2_b32 v172, v8, v9 offset0:16 offset1:17
	ds_write2_b32 v172, v10, v11 offset0:18 offset1:19
	ds_write2_b32 v172, v12, v13 offset0:24 offset1:25
	ds_write2_b32 v172, v14, v15 offset0:26 offset1:27
	ds_write2_b32 v172, v16, v17 offset0:32 offset1:33
	ds_write2_b32 v172, v18, v19 offset0:34 offset1:35
	ds_write2_b32 v172, v20, v21 offset0:40 offset1:41
	ds_write2_b32 v172, v22, v23 offset0:42 offset1:43
	ds_write2_b32 v172, v24, v25 offset0:48 offset1:49
	ds_write2_b32 v172, v26, v27 offset0:50 offset1:51
	ds_write2_b32 v172, v28, v29 offset0:56 offset1:57
	ds_write2_b32 v172, v30, v31 offset0:58 offset1:59
	v_rcp_f32_e32 v43, v40
	s_nop 0
	v_mul_f32_e32 v40, v42, v43
	v_mul_f32_e32 v42, 0xbfb8aa3b, v66
	v_mul_f32_e32 v43, 0xbfb8aa3b, v44
	v_exp_f32_e32 v42, v42
	v_exp_f32_e32 v43, v43
	s_waitcnt lgkmcnt(0)
	s_barrier
	v_pk_add_f32 v[42:43], v[42:43], 1.0 op_sel_hi:[1,0]
	v_lshlrev_b32_e32 v79, 16, v56
	global_load_dwordx4 v[16:19], v[80:81], off offset:48
	global_load_dwordx4 v[20:23], v[80:81], off offset:32
	global_load_dwordx4 v[24:27], v[80:81], off offset:16
	global_load_dwordx4 v[28:31], v[80:81], off
	global_load_dwordx4 v[0:3], v[80:81], off offset:112
	global_load_dwordx4 v[4:7], v[80:81], off offset:96
	global_load_dwordx4 v[8:11], v[80:81], off offset:80
	global_load_dwordx4 v[12:15], v[80:81], off offset:64
	v_and_b32_e32 v80, 0xffff0000, v56
	v_mul_f32_e32 v56, 0xbfb8aa3b, v79
	v_rcp_f32_e32 v45, v43
	s_nop 0
	v_mul_f32_e32 v43, v44, v45
	v_mul_f32_e32 v44, 0xbfb8aa3b, v71
	v_mul_f32_e32 v45, 0xbfb8aa3b, v58
	v_exp_f32_e32 v44, v44
	v_exp_f32_e32 v45, v45
	v_rcp_f32_e32 v67, v42
	s_nop 0
	v_mul_f32_e32 v42, v66, v67
	v_pk_add_f32 v[44:45], v[44:45], 1.0 op_sel_hi:[1,0]
	v_lshlrev_b32_e32 v83, 16, v54
	v_and_b32_e32 v54, 0xffff0000, v54
	v_lshlrev_b32_e32 v113, 16, v55
	v_and_b32_e32 v124, 0xffff0000, v55
	v_rcp_f32_e32 v59, v45
	s_nop 0
	v_mul_f32_e32 v45, v58, v59
	v_mul_f32_e32 v59, 0xbfb8aa3b, v57
	v_mul_f32_e32 v58, 0xbfb8aa3b, v77
	v_exp_f32_e32 v58, v58
	v_exp_f32_e32 v59, v59
	s_nop 0
	v_pk_add_f32 v[58:59], v[58:59], 1.0 op_sel_hi:[1,0]
	v_rcp_f32_e32 v66, v44
	s_nop 0
	v_mul_f32_e32 v44, v71, v66
	v_lshlrev_b32_e32 v88, 16, v53
	v_rcp_f32_e32 v66, v59
	s_nop 0
	v_mul_f32_e32 v57, v57, v66
	v_and_b32_e32 v53, 0xffff0000, v53
	v_exp_f32_e32 v66, v56
	v_mul_f32_e32 v56, 0xbfb8aa3b, v80
	v_exp_f32_e32 v67, v56
	v_rcp_f32_e32 v56, v58
	s_nop 0
	v_mul_f32_e32 v56, v77, v56
	v_lshlrev_b32_e32 v89, 16, v52
	ds_read2_b32 v[46:47], v158 offset0:6 offset1:7
	ds_read2_b32 v[60:61], v158 offset0:4 offset1:5
	ds_read2_b32 v[62:63], v158 offset0:2 offset1:3
	ds_read2_b32 v[64:65], v158 offset1:1
	v_pk_add_f32 v[66:67], v[66:67], 1.0 op_sel_hi:[1,0]
	ds_read2_b32 v[68:69], v158 offset0:14 offset1:15
	ds_read2_b32 v[70:71], v158 offset0:12 offset1:13
	ds_read2_b32 v[72:73], v158 offset0:10 offset1:11
	ds_read2_b32 v[74:75], v158 offset0:8 offset1:9
	s_waitcnt lgkmcnt(4)
	v_add_f32_e32 v32, 0, v64
	v_add_f32_e32 v32, v32, v65
	v_add_f32_e32 v32, v32, v62
	v_rcp_f32_e32 v59, v67
	s_nop 0
	v_mul_f32_e32 v59, v80, v59
	v_add_f32_e32 v32, v32, v63
	v_rcp_f32_e32 v58, v66
	s_nop 0
	v_mul_f32_e32 v58, v79, v58
	v_mul_f32_e32 v66, 0xbfb8aa3b, v78
	v_mul_f32_e32 v67, 0xbfb8aa3b, v76
	v_exp_f32_e32 v66, v66
	v_exp_f32_e32 v67, v67
	v_add_f32_e32 v32, v32, v60
	v_add_f32_e32 v32, v32, v61
	v_add_f32_e32 v32, v32, v46
	v_pk_add_f32 v[66:67], v[66:67], 1.0 op_sel_hi:[1,0]
	v_add_f32_e32 v32, v32, v47
	s_waitcnt lgkmcnt(0)
	v_add_f32_e32 v32, v32, v74
	v_add_f32_e32 v32, v32, v75
	v_add_f32_e32 v32, v32, v72
	v_rcp_f32_e32 v77, v67
	s_nop 0
	v_mul_f32_e32 v67, v76, v77
	v_mul_f32_e32 v76, 0xbfb8aa3b, v83
	v_mul_f32_e32 v77, 0xbfb8aa3b, v54
	v_exp_f32_e32 v76, v76
	v_exp_f32_e32 v77, v77
	v_rcp_f32_e32 v79, v66
	s_nop 0
	v_mul_f32_e32 v66, v78, v79
	v_pk_add_f32 v[76:77], v[76:77], 1.0 op_sel_hi:[1,0]
	v_add_f32_e32 v32, v32, v73
	v_add_f32_e32 v32, v32, v70
	v_add_f32_e32 v32, v32, v71
	v_add_f32_e32 v32, v32, v68
	v_mul_f32_e32 v78, 0xbfb8aa3b, v88
	v_mul_f32_e32 v79, 0xbfb8aa3b, v53
	v_rcp_f32_e32 v55, v77
	s_nop 0
	v_mul_f32_e32 v55, v54, v55
	v_exp_f32_e32 v78, v78
	v_exp_f32_e32 v79, v79
	s_nop 0
	v_pk_add_f32 v[78:79], v[78:79], 1.0 op_sel_hi:[1,0]
	v_rcp_f32_e32 v54, v76
	s_nop 0
	v_mul_f32_e32 v54, v83, v54
	v_add_f32_e32 v32, v32, v69
	v_rcp_f32_e32 v77, v79
	s_nop 0
	v_mul_f32_e32 v77, v53, v77
	s_mov_b32 s37, 0
	v_and_b32_e32 v79, 0xffff0000, v52
	v_mul_f32_e32 v52, 0xbfb8aa3b, v89
	v_mul_f32_e32 v53, 0xbfb8aa3b, v79
	v_exp_f32_e32 v52, v52
	v_exp_f32_e32 v53, v53
	v_rcp_f32_e32 v76, v78
	s_nop 0
	v_mul_f32_e32 v76, v88, v76
	ds_read2_b32 v[80:81], v158 offset0:22 offset1:23
	ds_read2_b32 v[82:83], v158 offset0:20 offset1:21
	ds_read2_b32 v[84:85], v158 offset0:18 offset1:19
	ds_read2_b32 v[86:87], v158 offset0:16 offset1:17
	v_lshl_add_u64 v[34:35], v[34:35], 0, s[36:37]
	v_pk_add_f32 v[52:53], v[52:53], 1.0 op_sel_hi:[1,0]
	v_mov_b32_e32 v115, v33
	s_waitcnt lgkmcnt(0)
	v_add_f32_e32 v32, v32, v86
	v_add_f32_e32 v32, v32, v87
	v_add_f32_e32 v32, v32, v84
	v_rcp_f32_e32 v78, v53
	s_nop 0
	v_mul_f32_e32 v79, v79, v78
	v_add_f32_e32 v32, v32, v85
	v_rcp_f32_e32 v78, v52
	s_nop 0
	v_mul_f32_e32 v78, v89, v78
	v_mul_f32_e32 v52, 0xbfb8aa3b, v113
	v_mul_f32_e32 v53, 0xbfb8aa3b, v124
	v_exp_f32_e32 v52, v52
	v_exp_f32_e32 v53, v53
	v_add_f32_e32 v32, v32, v82
	v_add_f32_e32 v32, v32, v83
	v_add_f32_e32 v32, v32, v80
	v_pk_add_f32 v[88:89], v[52:53], 1.0 op_sel_hi:[1,0]
	ds_read2_b32 v[90:91], v158 offset0:30 offset1:31
	ds_read2_b32 v[52:53], v158 offset0:28 offset1:29
	ds_read2_b32 v[92:93], v158 offset0:26 offset1:27
	ds_read2_b32 v[94:95], v158 offset0:24 offset1:25
	v_add_f32_e32 v32, v32, v81
	s_waitcnt lgkmcnt(0)
	v_add_f32_e32 v32, v32, v94
	v_add_f32_e32 v32, v32, v95
	v_add_f32_e32 v32, v32, v92
	v_add_f32_e32 v32, v32, v93
	v_add_f32_e32 v32, v32, v52
	v_add_f32_e32 v32, v32, v53
	v_add_f32_e32 v32, v32, v90
	v_add_f32_e32 v32, v32, v91
	ds_bpermute_b32 v97, v157, v32
	s_waitcnt lgkmcnt(0)
	v_add_f32_e32 v32, v32, v97
	ds_bpermute_b32 v97, v156, v32
	v_lshl_add_u64 v[34:35], v[34:35], 0, v[114:115]
	s_waitcnt lgkmcnt(0)
	v_add_f32_e32 v32, v32, v97
	v_mul_f32_e32 v32, 0x3c000000, v32
	v_pk_add_f32 v[64:65], v[64:65], v[32:33] op_sel_hi:[1,0] neg_lo:[0,1] neg_hi:[0,1]
	v_pk_add_f32 v[62:63], v[62:63], v[32:33] op_sel_hi:[1,0] neg_lo:[0,1] neg_hi:[0,1]
	v_pk_mul_f32 v[96:97], v[64:65], v[64:65]
	v_pk_mul_f32 v[98:99], v[62:63], v[62:63]
	v_pk_add_f32 v[100:101], v[60:61], v[32:33] op_sel_hi:[1,0] neg_lo:[0,1] neg_hi:[0,1]
	v_pk_add_f32 v[104:105], v[46:47], v[32:33] op_sel_hi:[1,0] neg_lo:[0,1] neg_hi:[0,1]
	v_pk_add_f32 v[74:75], v[74:75], v[32:33] op_sel_hi:[1,0] neg_lo:[0,1] neg_hi:[0,1]
	v_pk_add_f32 v[72:73], v[72:73], v[32:33] op_sel_hi:[1,0] neg_lo:[0,1] neg_hi:[0,1]
	v_pk_add_f32 v[70:71], v[70:71], v[32:33] op_sel_hi:[1,0] neg_lo:[0,1] neg_hi:[0,1]
	v_pk_add_f32 v[68:69], v[68:69], v[32:33] op_sel_hi:[1,0] neg_lo:[0,1] neg_hi:[0,1]
	v_pk_add_f32 v[86:87], v[86:87], v[32:33] op_sel_hi:[1,0] neg_lo:[0,1] neg_hi:[0,1]
	v_pk_add_f32 v[84:85], v[84:85], v[32:33] op_sel_hi:[1,0] neg_lo:[0,1] neg_hi:[0,1]
	v_pk_add_f32 v[82:83], v[82:83], v[32:33] op_sel_hi:[1,0] neg_lo:[0,1] neg_hi:[0,1]
	v_pk_add_f32 v[80:81], v[80:81], v[32:33] op_sel_hi:[1,0] neg_lo:[0,1] neg_hi:[0,1]
	v_pk_add_f32 v[94:95], v[94:95], v[32:33] op_sel_hi:[1,0] neg_lo:[0,1] neg_hi:[0,1]
	v_pk_add_f32 v[60:61], v[92:93], v[32:33] op_sel_hi:[1,0] neg_lo:[0,1] neg_hi:[0,1]
	v_pk_add_f32 v[52:53], v[52:53], v[32:33] op_sel_hi:[1,0] neg_lo:[0,1] neg_hi:[0,1]
	v_pk_add_f32 v[46:47], v[90:91], v[32:33] op_sel_hi:[1,0] neg_lo:[0,1] neg_hi:[0,1]
	v_add_f32_e32 v32, v96, v97
	v_add_f32_e32 v32, v98, v32
	v_pk_mul_f32 v[102:103], v[100:101], v[100:101]
	v_add_f32_e32 v32, v99, v32
	v_add_f32_e32 v32, v102, v32
	v_pk_mul_f32 v[106:107], v[104:105], v[104:105]
	v_add_f32_e32 v32, v103, v32
	v_add_f32_e32 v32, v106, v32
	v_pk_mul_f32 v[108:109], v[74:75], v[74:75]
	v_add_f32_e32 v32, v107, v32
	v_add_f32_e32 v32, v108, v32
	v_pk_mul_f32 v[110:111], v[72:73], v[72:73]
	v_add_f32_e32 v32, v109, v32
	v_add_f32_e32 v32, v110, v32
	v_pk_mul_f32 v[114:115], v[70:71], v[70:71]
	v_add_f32_e32 v32, v111, v32
	v_add_f32_e32 v32, v114, v32
	v_pk_mul_f32 v[116:117], v[68:69], v[68:69]
	v_add_f32_e32 v32, v115, v32
	v_add_f32_e32 v32, v116, v32
	v_pk_mul_f32 v[118:119], v[86:87], v[86:87]
	v_add_f32_e32 v32, v117, v32
	v_add_f32_e32 v32, v118, v32
	v_pk_mul_f32 v[120:121], v[84:85], v[84:85]
	v_add_f32_e32 v32, v119, v32
	v_add_f32_e32 v32, v120, v32
	v_pk_mul_f32 v[122:123], v[82:83], v[82:83]
	v_add_f32_e32 v32, v121, v32
	v_add_f32_e32 v32, v122, v32
	v_pk_mul_f32 v[126:127], v[80:81], v[80:81]
	v_add_f32_e32 v32, v123, v32
	v_add_f32_e32 v32, v126, v32
	v_pk_mul_f32 v[128:129], v[94:95], v[94:95]
	v_add_f32_e32 v32, v127, v32
	v_add_f32_e32 v32, v128, v32
	v_pk_mul_f32 v[92:93], v[60:61], v[60:61]
	v_add_f32_e32 v32, v129, v32
	v_add_f32_e32 v32, v92, v32
	v_pk_mul_f32 v[130:131], v[52:53], v[52:53]
	v_add_f32_e32 v32, v93, v32
	v_add_f32_e32 v32, v130, v32
	v_pk_mul_f32 v[90:91], v[46:47], v[46:47]
	v_add_f32_e32 v32, v131, v32
	v_add_f32_e32 v32, v90, v32
	v_add_f32_e32 v32, v91, v32
	ds_bpermute_b32 v90, v157, v32
	s_mov_b32 s0, 0xf800000
	v_rcp_f32_e32 v91, v89
	s_nop 0
	v_mul_f32_e32 v89, v124, v91
	s_waitcnt lgkmcnt(0)
	v_add_f32_e32 v32, v32, v90
	ds_bpermute_b32 v90, v156, v32
	s_waitcnt lgkmcnt(0)
	v_add_f32_e32 v32, v32, v90
	v_mov_b32_e32 v90, 0x358637bd
	v_fmac_f32_e32 v90, 0x3c000000, v32
	v_mul_f32_e32 v32, 0x4f800000, v90
	v_cmp_gt_f32_e64 s[0:1], s0, v90
	s_nop 1
	v_cndmask_b32_e64 v32, v90, v32, s[0:1]
	v_sqrt_f32_e32 v90, v32
	v_readlane_b32 s5, v254, 1
	v_add_u32_e32 v93, -1, v90
	v_fma_f32 v96, -v93, v90, v32
	v_cmp_ge_f32_e64 s[4:5], 0, v96
	v_add_u32_e32 v96, 1, v90
	s_nop 1
	v_cndmask_b32_e64 v93, v90, v93, s[4:5]
	v_fma_f32 v90, -v96, v90, v32
	v_cmp_lt_f32_e64 s[4:5], 0, v90
	v_rcp_f32_e32 v91, v88
	s_nop 0
	v_mul_f32_e32 v88, v113, v91
	s_movk_i32 s2, 0x37ff
	v_cndmask_b32_e64 v90, v93, v96, s[4:5]
	v_mul_f32_e32 v93, 0x37800000, v90
	v_cndmask_b32_e64 v90, v90, v93, s[0:1]
	v_mov_b32_e32 v93, 0x260
	v_cmp_class_f32_e64 s[0:1], v32, v93
	s_nop 1
	v_cndmask_b32_e64 v32, v90, v32, s[0:1]
	v_rcp_f32_e32 v32, v32
	s_nop 0
	v_pk_mul_f32 v[64:65], v[64:65], v[32:33] op_sel_hi:[1,0]
	s_waitcnt vmcnt(4)
	v_pk_mul_f32 v[28:29], v[28:29], v[64:65]
	s_nop 0
	v_pk_mul_f32 v[28:29], v[40:41], v[28:29]
	v_pk_mul_f32 v[40:41], v[62:63], v[32:33] op_sel_hi:[1,0]
	s_nop 0
	v_pk_mul_f32 v[30:31], v[30:31], v[40:41]
	s_nop 0
	v_pk_mul_f32 v[30:31], v[38:39], v[30:31]
	v_pk_mul_f32 v[38:39], v[100:101], v[32:33] op_sel_hi:[1,0]
	s_nop 0
	v_pk_mul_f32 v[24:25], v[24:25], v[38:39]
	s_nop 0
	v_pk_mul_f32 v[36:37], v[36:37], v[24:25]
	v_pk_mul_f32 v[24:25], v[104:105], v[32:33] op_sel_hi:[1,0]
	s_nop 0
	v_pk_mul_f32 v[24:25], v[26:27], v[24:25]
	v_cvt_pk_bf16_f32 v26, v36, v37
	v_pk_mul_f32 v[38:39], v[42:43], v[24:25]
	v_cvt_pk_bf16_f32 v24, v28, v29
	v_cvt_pk_bf16_f32 v25, v30, v31
	v_cvt_pk_bf16_f32 v27, v38, v39
	global_store_dwordx4 v[34:35], v[24:27], off
	s_nop 1
	v_pk_mul_f32 v[24:25], v[74:75], v[32:33] op_sel_hi:[1,0]
	s_nop 0
	v_pk_mul_f32 v[20:21], v[20:21], v[24:25]
	v_pk_mul_f32 v[24:25], v[72:73], v[32:33] op_sel_hi:[1,0]
	v_pk_mul_f32 v[20:21], v[58:59], v[20:21]
	v_pk_mul_f32 v[22:23], v[22:23], v[24:25]
	v_pk_mul_f32 v[24:25], v[70:71], v[32:33] op_sel_hi:[1,0]
	v_pk_mul_f32 v[22:23], v[56:57], v[22:23]
	v_pk_mul_f32 v[16:17], v[16:17], v[24:25]
	s_nop 0
	v_pk_mul_f32 v[24:25], v[44:45], v[16:17]
	v_pk_mul_f32 v[16:17], v[68:69], v[32:33] op_sel_hi:[1,0]
	s_nop 0
	v_pk_mul_f32 v[16:17], v[18:19], v[16:17]
	v_cvt_pk_bf16_f32 v18, v24, v25
	v_pk_mul_f32 v[26:27], v[66:67], v[16:17]
	v_cvt_pk_bf16_f32 v16, v20, v21
	v_cvt_pk_bf16_f32 v17, v22, v23
	v_cvt_pk_bf16_f32 v19, v26, v27
	global_store_dwordx4 v[34:35], v[16:19], off offset:16
	v_lshlrev_b32_e32 v20, 16, v48
	v_and_b32_e32 v21, 0xffff0000, v48
	v_pk_mul_f32 v[16:17], v[86:87], v[32:33] op_sel_hi:[1,0]
	s_waitcnt vmcnt(2)
	v_pk_mul_f32 v[12:13], v[12:13], v[16:17]
	v_pk_mul_f32 v[16:17], v[84:85], v[32:33] op_sel_hi:[1,0]
	v_pk_mul_f32 v[12:13], v[78:79], v[12:13]
	v_pk_mul_f32 v[14:15], v[14:15], v[16:17]
	v_pk_mul_f32 v[16:17], v[82:83], v[32:33] op_sel_hi:[1,0]
	v_pk_mul_f32 v[14:15], v[76:77], v[14:15]
	v_pk_mul_f32 v[8:9], v[8:9], v[16:17]
	s_nop 0
	v_pk_mul_f32 v[16:17], v[54:55], v[8:9]
	v_pk_mul_f32 v[8:9], v[80:81], v[32:33] op_sel_hi:[1,0]
	s_nop 0
	v_pk_mul_f32 v[8:9], v[10:11], v[8:9]
	v_mul_f32_e32 v10, 0xbfb8aa3b, v20
	v_mul_f32_e32 v11, 0xbfb8aa3b, v21
	v_exp_f32_e32 v10, v10
	v_exp_f32_e32 v11, v11
	v_pk_mul_f32 v[18:19], v[88:89], v[8:9]
	v_cvt_pk_bf16_f32 v8, v12, v13
	v_cvt_pk_bf16_f32 v9, v14, v15
	v_pk_add_f32 v[12:13], v[10:11], 1.0 op_sel_hi:[1,0]
	v_cvt_pk_bf16_f32 v10, v16, v17
	v_cvt_pk_bf16_f32 v11, v18, v19
	global_store_dwordx4 v[34:35], v[8:11], off offset:32
	v_and_b32_e32 v16, 0xffff0000, v49
	s_nop 0
	v_rcp_f32_e32 v9, v13
	s_nop 0
	v_mul_f32_e32 v9, v21, v9
	v_lshlrev_b32_e32 v15, 16, v49
	v_mul_f32_e32 v10, 0xbfb8aa3b, v15
	v_mul_f32_e32 v11, 0xbfb8aa3b, v16
	v_exp_f32_e32 v10, v10
	v_exp_f32_e32 v11, v11
	v_rcp_f32_e32 v8, v12
	s_nop 0
	v_mul_f32_e32 v8, v20, v8
	v_pk_mul_f32 v[12:13], v[94:95], v[32:33] op_sel_hi:[1,0]
	v_pk_add_f32 v[10:11], v[10:11], 1.0 op_sel_hi:[1,0]
	v_pk_mul_f32 v[4:5], v[4:5], v[12:13]
	v_pk_mul_f32 v[4:5], v[8:9], v[4:5]
	v_rcp_f32_e32 v9, v11
	s_nop 0
	v_mul_f32_e32 v9, v16, v9
	v_lshlrev_b32_e32 v16, 16, v50
	v_and_b32_e32 v17, 0xffff0000, v50
	v_mul_f32_e32 v12, 0xbfb8aa3b, v16
	v_mul_f32_e32 v13, 0xbfb8aa3b, v17
	v_exp_f32_e32 v12, v12
	v_exp_f32_e32 v13, v13
	v_rcp_f32_e32 v8, v10
	s_nop 0
	v_mul_f32_e32 v8, v15, v8
	v_pk_add_f32 v[10:11], v[12:13], 1.0 op_sel_hi:[1,0]
	s_nop 0
	v_pk_mul_f32 v[12:13], v[60:61], v[32:33] op_sel_hi:[1,0]
	s_nop 0
	v_pk_mul_f32 v[6:7], v[6:7], v[12:13]
	s_nop 0
	v_pk_mul_f32 v[6:7], v[8:9], v[6:7]
	v_rcp_f32_e32 v9, v11
	s_nop 0
	v_mul_f32_e32 v9, v17, v9
	v_lshlrev_b32_e32 v15, 16, v51
	v_and_b32_e32 v17, 0xffff0000, v51
	v_mul_f32_e32 v12, 0xbfb8aa3b, v15
	v_mul_f32_e32 v13, 0xbfb8aa3b, v17
	v_exp_f32_e32 v12, v12
	v_exp_f32_e32 v13, v13
	v_rcp_f32_e32 v8, v10
	s_nop 0
	v_mul_f32_e32 v8, v16, v8
	v_pk_add_f32 v[10:11], v[12:13], 1.0 op_sel_hi:[1,0]
	s_nop 0
	v_pk_mul_f32 v[12:13], v[52:53], v[32:33] op_sel_hi:[1,0]
	s_nop 0
	v_pk_mul_f32 v[0:1], v[0:1], v[12:13]
	s_nop 0
	v_pk_mul_f32 v[8:9], v[8:9], v[0:1]
	v_rcp_f32_e32 v1, v11
	s_nop 0
	v_mul_f32_e32 v1, v17, v1
	v_rcp_f32_e32 v0, v10
	s_nop 0
	v_mul_f32_e32 v0, v15, v0
	v_pk_mul_f32 v[10:11], v[46:47], v[32:33] op_sel_hi:[1,0]
	s_mov_b64 s[0:1], 0x3300000
	v_pk_mul_f32 v[2:3], v[2:3], v[10:11]
	s_nop 0
	v_pk_mul_f32 v[10:11], v[0:1], v[2:3]
	v_cvt_pk_bf16_f32 v0, v4, v5
	v_cvt_pk_bf16_f32 v1, v6, v7
	v_cvt_pk_bf16_f32 v2, v8, v9
	v_cvt_pk_bf16_f32 v3, v10, v11
	global_store_dwordx4 v[34:35], v[0:3], off offset:48
	v_lshl_add_u32 v5, s52, 9, v226
	s_waitcnt lgkmcnt(0)
	s_barrier
	s_lshr_b32 s0, s88, 5
	s_lshl_b32 s1, s0, 3
	s_add_i32 s1, s1, s53
	s_lshl_b32 s2, s1, 8
	s_lshl_b32 s3, s52, 3
	s_add_i32 s2, s2, s3
	v_readlane_b32 s8, v254, 2
	v_readlane_b32 s9, v254, 3
	v_lshrrev_b32_e32 v22, 6, v226
	v_add_u32_e32 v23, s2, v22
	v_and_b32_e32 v32, 63, v226
	v_lshlrev_b32_e32 v32, 4, v32
	v_bfe_u32 v33, v226, 3, 3
	v_lshlrev_b32_e32 v33, 2, v33
	v_lshl_add_u32 v0, v23, 5, v33
	v_add_u32_e32 v0, 0x3300000, v0
	v_add_u32_e32 v1, 0x1000, v0
	v_add_u32_e32 v2, 0x80000, v0
	v_add_u32_e32 v3, 0x81000, v0
	v_add_u32_e32 v4, 0x100000, v0
	v_add_u32_e32 v5, 0x101000, v0
	v_lshl_add_u32 v6, v23, 10, v32
	v_add_u32_e32 v6, 0xb500000, v6
	v_add_u32_e32 v7, s3, v22
	v_lshl_add_u32 v7, v7, 11, v32
	s_lshl_b32 s2, s1, 20
	s_add_u32 s8, s8, s2
	s_addc_u32 s9, s9, 0
	global_load_dword v60, v0, s[96:97]
	global_load_dword v61, v2, s[96:97]
	global_load_dword v62, v4, s[96:97]
	global_load_dwordx4 v[48:51], v6, s[96:97]
	v_add_u32_e32 v8, 0x1000000, v6
	global_load_dwordx4 v[52:55], v8, s[96:97]
	v_add_u32_e32 v8, 0x2000000, v6
	global_load_dwordx4 v[56:59], v8, s[96:97]
	global_load_dword v76, v0, s[96:97] offset:1024
	global_load_dword v77, v2, s[96:97] offset:1024
	global_load_dword v78, v4, s[96:97] offset:1024
	v_add_u32_e32 v8, 0x8000, v6
	global_load_dwordx4 v[64:67], v8, s[96:97]
	v_add_u32_e32 v8, 0x1008000, v6
	global_load_dwordx4 v[68:71], v8, s[96:97]
	v_add_u32_e32 v8, 0x2008000, v6
	global_load_dwordx4 v[72:75], v8, s[96:97]
	global_load_dword v92, v0, s[96:97] offset:2048
	global_load_dword v93, v2, s[96:97] offset:2048
	global_load_dword v94, v4, s[96:97] offset:2048
	v_add_u32_e32 v8, 0x10000, v6
	global_load_dwordx4 v[80:83], v8, s[96:97]
	v_add_u32_e32 v8, 0x1010000, v6
	global_load_dwordx4 v[84:87], v8, s[96:97]
	v_add_u32_e32 v8, 0x2010000, v6
	global_load_dwordx4 v[88:91], v8, s[96:97]
	global_load_dword v108, v0, s[96:97] offset:3072
	global_load_dword v109, v2, s[96:97] offset:3072
	global_load_dword v110, v4, s[96:97] offset:3072
	v_add_u32_e32 v8, 0x18000, v6
	global_load_dwordx4 v[96:99], v8, s[96:97]
	v_add_u32_e32 v8, 0x1018000, v6
	global_load_dwordx4 v[100:103], v8, s[96:97]
	v_add_u32_e32 v8, 0x2018000, v6
	global_load_dwordx4 v[104:107], v8, s[96:97]
	global_load_dword v140, v1, s[96:97]
	global_load_dword v141, v3, s[96:97]
	global_load_dword v142, v5, s[96:97]
	v_add_u32_e32 v8, 0x20000, v6
	global_load_dwordx4 v[128:131], v8, s[96:97]
	v_add_u32_e32 v8, 0x1020000, v6
	global_load_dwordx4 v[132:135], v8, s[96:97]
	v_add_u32_e32 v8, 0x2020000, v6
	global_load_dwordx4 v[136:139], v8, s[96:97]
	global_load_dword v164, v1, s[96:97] offset:1024
	global_load_dword v165, v3, s[96:97] offset:1024
	global_load_dword v166, v5, s[96:97] offset:1024
	v_add_u32_e32 v8, 0x28000, v6
	global_load_dwordx4 v[152:155], v8, s[96:97]
	v_add_u32_e32 v8, 0x1028000, v6
	global_load_dwordx4 v[156:159], v8, s[96:97]
	v_add_u32_e32 v8, 0x2028000, v6
	global_load_dwordx4 v[160:163], v8, s[96:97]
	global_load_dword v218, v1, s[96:97] offset:2048
	global_load_dword v219, v3, s[96:97] offset:2048
	global_load_dword v220, v5, s[96:97] offset:2048
	v_add_u32_e32 v8, 0x30000, v6
	global_load_dwordx4 v[206:209], v8, s[96:97]
	v_add_u32_e32 v8, 0x1030000, v6
	global_load_dwordx4 v[210:213], v8, s[96:97]
	v_add_u32_e32 v8, 0x2030000, v6
	global_load_dwordx4 v[214:217], v8, s[96:97]
	global_load_dword v244, v1, s[96:97] offset:3072
	global_load_dword v245, v3, s[96:97] offset:3072
	global_load_dword v246, v5, s[96:97] offset:3072
	v_add_u32_e32 v8, 0x38000, v6
	global_load_dwordx4 v[232:235], v8, s[96:97]
	v_add_u32_e32 v8, 0x1038000, v6
	global_load_dwordx4 v[236:239], v8, s[96:97]
	v_add_u32_e32 v8, 0x2038000, v6
	global_load_dwordx4 v[240:243], v8, s[96:97]
	s_waitcnt vmcnt(42)
	v_max3_f32 v5, v60, v61, v62
	v_sub_f32_e32 v9, v60, v5
	v_sub_f32_e32 v40, v61, v5
	v_and_b32_e32 v27, 0xffff0000, v49
	v_lshlrev_b32_e32 v28, 16, v49
	v_sub_f32_e32 v5, v62, v5
	v_lshlrev_b32_e32 v24, 16, v52
	v_and_b32_e32 v11, 0xffff0000, v52
	v_lshlrev_b32_e32 v38, 16, v56
	v_and_b32_e32 v39, 0xffff0000, v56
	v_lshlrev_b32_e32 v26, 16, v53
	v_and_b32_e32 v29, 0xffff0000, v53
	v_lshlrev_b32_e32 v14, 16, v57
	v_and_b32_e32 v15, 0xffff0000, v57
	v_lshlrev_b32_e32 v18, 16, v58
	v_and_b32_e32 v19, 0xffff0000, v58
	v_mul_f32_e32 v9, 0x3fb8aa3b, v9
	v_mul_f32_e32 v20, 0x3fb8aa3b, v40
	v_and_b32_e32 v35, 0xffff0000, v51
	v_lshlrev_b32_e32 v36, 16, v51
	v_lshlrev_b32_e32 v30, 16, v54
	v_and_b32_e32 v13, 0xffff0000, v54
	v_lshlrev_b32_e32 v34, 16, v55
	v_and_b32_e32 v37, 0xffff0000, v55
	v_lshlrev_b32_e32 v16, 16, v59
	v_and_b32_e32 v17, 0xffff0000, v59
	v_mul_f32_e32 v5, 0x3fb8aa3b, v5
	v_exp_f32_e32 v21, v9
	v_exp_f32_e32 v20, v20
	v_exp_f32_e32 v5, v5
	v_and_b32_e32 v25, 0xffff0000, v48
	v_lshlrev_b32_e32 v10, 16, v48
	v_add_f32_e32 v9, v21, v20
	v_add_f32_e32 v9, v5, v9
	v_and_b32_e32 v31, 0xffff0000, v50
	v_rcp_f32_e32 v40, v9
	s_nop 0
	v_lshlrev_b32_e32 v12, 16, v50
	v_pk_mul_f32 v[20:21], v[20:21], v[40:41] op_sel_hi:[1,0]
	v_mul_f32_e32 v42, v5, v40
	v_pk_mul_f32 v[10:11], v[20:21], v[10:11] op_sel:[1,0] op_sel_hi:[0,1]
	v_pk_mul_f32 v[28:29], v[20:21], v[28:29] op_sel:[1,0] op_sel_hi:[0,1]
	v_pk_mul_f32 v[12:13], v[20:21], v[12:13] op_sel:[1,0] op_sel_hi:[0,1]
	v_pk_mul_f32 v[36:37], v[20:21], v[36:37] op_sel:[1,0] op_sel_hi:[0,1]
	v_pk_fma_f32 v[10:11], v[20:21], v[24:25], v[10:11]
	v_pk_fma_f32 v[24:25], v[20:21], v[26:27], v[28:29]
	v_pk_fma_f32 v[12:13], v[20:21], v[30:31], v[12:13]
	v_pk_fma_f32 v[20:21], v[20:21], v[34:35], v[36:37]
	v_pk_fma_f32 v[10:11], v[42:43], v[38:39], v[10:11] op_sel_hi:[0,1,1]
	v_pk_fma_f32 v[14:15], v[42:43], v[14:15], v[24:25] op_sel_hi:[0,1,1]
	v_pk_fma_f32 v[12:13], v[42:43], v[18:19], v[12:13] op_sel_hi:[0,1,1]
	v_pk_fma_f32 v[16:17], v[42:43], v[16:17], v[20:21] op_sel_hi:[0,1,1]
	v_cvt_pk_bf16_f32 v10, v10, v11
	v_cvt_pk_bf16_f32 v11, v14, v15
	v_cvt_pk_bf16_f32 v12, v12, v13
	v_cvt_pk_bf16_f32 v13, v16, v17
	global_store_dwordx4 v7, v[10:13], s[8:9] offset:1024
	s_waitcnt vmcnt(37)
	v_max3_f32 v5, v76, v77, v78
	v_sub_f32_e32 v9, v76, v5
	v_sub_f32_e32 v40, v77, v5
	v_and_b32_e32 v27, 0xffff0000, v65
	v_lshlrev_b32_e32 v28, 16, v65
	v_sub_f32_e32 v5, v78, v5
	v_lshlrev_b32_e32 v24, 16, v68
	v_and_b32_e32 v11, 0xffff0000, v68
	v_lshlrev_b32_e32 v38, 16, v72
	v_and_b32_e32 v39, 0xffff0000, v72
	v_lshlrev_b32_e32 v26, 16, v69
	v_and_b32_e32 v29, 0xffff0000, v69
	v_lshlrev_b32_e32 v14, 16, v73
	v_and_b32_e32 v15, 0xffff0000, v73
	v_lshlrev_b32_e32 v18, 16, v74
	v_and_b32_e32 v19, 0xffff0000, v74
	v_mul_f32_e32 v9, 0x3fb8aa3b, v9
	v_mul_f32_e32 v20, 0x3fb8aa3b, v40
	v_and_b32_e32 v35, 0xffff0000, v67
	v_lshlrev_b32_e32 v36, 16, v67
	v_lshlrev_b32_e32 v30, 16, v70
	v_and_b32_e32 v13, 0xffff0000, v70
	v_lshlrev_b32_e32 v34, 16, v71
	v_and_b32_e32 v37, 0xffff0000, v71
	v_lshlrev_b32_e32 v16, 16, v75
	v_and_b32_e32 v17, 0xffff0000, v75
	v_mul_f32_e32 v5, 0x3fb8aa3b, v5
	v_exp_f32_e32 v21, v9
	v_exp_f32_e32 v20, v20
	v_exp_f32_e32 v5, v5
	v_and_b32_e32 v25, 0xffff0000, v64
	v_lshlrev_b32_e32 v10, 16, v64
	v_add_f32_e32 v9, v21, v20
	v_add_f32_e32 v9, v5, v9
	v_and_b32_e32 v31, 0xffff0000, v66
	v_rcp_f32_e32 v40, v9
	s_nop 0
	v_lshlrev_b32_e32 v12, 16, v66
	v_pk_mul_f32 v[20:21], v[20:21], v[40:41] op_sel_hi:[1,0]
	v_mul_f32_e32 v42, v5, v40
	v_pk_mul_f32 v[10:11], v[20:21], v[10:11] op_sel:[1,0] op_sel_hi:[0,1]
	v_pk_mul_f32 v[28:29], v[20:21], v[28:29] op_sel:[1,0] op_sel_hi:[0,1]
	v_pk_mul_f32 v[12:13], v[20:21], v[12:13] op_sel:[1,0] op_sel_hi:[0,1]
	v_pk_mul_f32 v[36:37], v[20:21], v[36:37] op_sel:[1,0] op_sel_hi:[0,1]
	v_pk_fma_f32 v[10:11], v[20:21], v[24:25], v[10:11]
	v_pk_fma_f32 v[24:25], v[20:21], v[26:27], v[28:29]
	v_pk_fma_f32 v[12:13], v[20:21], v[30:31], v[12:13]
	v_pk_fma_f32 v[20:21], v[20:21], v[34:35], v[36:37]
	v_pk_fma_f32 v[10:11], v[42:43], v[38:39], v[10:11] op_sel_hi:[0,1,1]
	v_pk_fma_f32 v[14:15], v[42:43], v[14:15], v[24:25] op_sel_hi:[0,1,1]
	v_pk_fma_f32 v[12:13], v[42:43], v[18:19], v[12:13] op_sel_hi:[0,1,1]
	v_pk_fma_f32 v[16:17], v[42:43], v[16:17], v[20:21] op_sel_hi:[0,1,1]
	v_cvt_pk_bf16_f32 v10, v10, v11
	v_cvt_pk_bf16_f32 v11, v14, v15
	v_cvt_pk_bf16_f32 v12, v12, v13
	v_cvt_pk_bf16_f32 v13, v16, v17
	v_add_u32_e32 v8, 0x10000, v7
	global_store_dwordx4 v8, v[10:13], s[8:9] offset:1024
	s_waitcnt vmcnt(32)
	v_max3_f32 v5, v92, v93, v94
	v_sub_f32_e32 v9, v92, v5
	v_sub_f32_e32 v40, v93, v5
	v_and_b32_e32 v27, 0xffff0000, v81
	v_lshlrev_b32_e32 v28, 16, v81
	v_sub_f32_e32 v5, v94, v5
	v_lshlrev_b32_e32 v24, 16, v84
	v_and_b32_e32 v11, 0xffff0000, v84
	v_lshlrev_b32_e32 v38, 16, v88
	v_and_b32_e32 v39, 0xffff0000, v88
	v_lshlrev_b32_e32 v26, 16, v85
	v_and_b32_e32 v29, 0xffff0000, v85
	v_lshlrev_b32_e32 v14, 16, v89
	v_and_b32_e32 v15, 0xffff0000, v89
	v_lshlrev_b32_e32 v18, 16, v90
	v_and_b32_e32 v19, 0xffff0000, v90
	v_mul_f32_e32 v9, 0x3fb8aa3b, v9
	v_mul_f32_e32 v20, 0x3fb8aa3b, v40
	v_and_b32_e32 v35, 0xffff0000, v83
	v_lshlrev_b32_e32 v36, 16, v83
	v_lshlrev_b32_e32 v30, 16, v86
	v_and_b32_e32 v13, 0xffff0000, v86
	v_lshlrev_b32_e32 v34, 16, v87
	v_and_b32_e32 v37, 0xffff0000, v87
	v_lshlrev_b32_e32 v16, 16, v91
	v_and_b32_e32 v17, 0xffff0000, v91
	v_mul_f32_e32 v5, 0x3fb8aa3b, v5
	v_exp_f32_e32 v21, v9
	v_exp_f32_e32 v20, v20
	v_exp_f32_e32 v5, v5
	v_and_b32_e32 v25, 0xffff0000, v80
	v_lshlrev_b32_e32 v10, 16, v80
	v_add_f32_e32 v9, v21, v20
	v_add_f32_e32 v9, v5, v9
	v_and_b32_e32 v31, 0xffff0000, v82
	v_rcp_f32_e32 v40, v9
	s_nop 0
	v_lshlrev_b32_e32 v12, 16, v82
	v_pk_mul_f32 v[20:21], v[20:21], v[40:41] op_sel_hi:[1,0]
	v_mul_f32_e32 v42, v5, v40
	v_pk_mul_f32 v[10:11], v[20:21], v[10:11] op_sel:[1,0] op_sel_hi:[0,1]
	v_pk_mul_f32 v[28:29], v[20:21], v[28:29] op_sel:[1,0] op_sel_hi:[0,1]
	v_pk_mul_f32 v[12:13], v[20:21], v[12:13] op_sel:[1,0] op_sel_hi:[0,1]
	v_pk_mul_f32 v[36:37], v[20:21], v[36:37] op_sel:[1,0] op_sel_hi:[0,1]
	v_pk_fma_f32 v[10:11], v[20:21], v[24:25], v[10:11]
	v_pk_fma_f32 v[24:25], v[20:21], v[26:27], v[28:29]
	v_pk_fma_f32 v[12:13], v[20:21], v[30:31], v[12:13]
	v_pk_fma_f32 v[20:21], v[20:21], v[34:35], v[36:37]
	v_pk_fma_f32 v[10:11], v[42:43], v[38:39], v[10:11] op_sel_hi:[0,1,1]
	v_pk_fma_f32 v[14:15], v[42:43], v[14:15], v[24:25] op_sel_hi:[0,1,1]
	v_pk_fma_f32 v[12:13], v[42:43], v[18:19], v[12:13] op_sel_hi:[0,1,1]
	v_pk_fma_f32 v[16:17], v[42:43], v[16:17], v[20:21] op_sel_hi:[0,1,1]
	v_cvt_pk_bf16_f32 v10, v10, v11
	v_cvt_pk_bf16_f32 v11, v14, v15
	v_cvt_pk_bf16_f32 v12, v12, v13
	v_cvt_pk_bf16_f32 v13, v16, v17
	v_add_u32_e32 v8, 0x20000, v7
	global_store_dwordx4 v8, v[10:13], s[8:9] offset:1024
	s_waitcnt vmcnt(27)
	v_max3_f32 v5, v108, v109, v110
	v_sub_f32_e32 v9, v108, v5
	v_sub_f32_e32 v40, v109, v5
	v_and_b32_e32 v27, 0xffff0000, v97
	v_lshlrev_b32_e32 v28, 16, v97
	v_sub_f32_e32 v5, v110, v5
	v_lshlrev_b32_e32 v24, 16, v100
	v_and_b32_e32 v11, 0xffff0000, v100
	v_lshlrev_b32_e32 v38, 16, v104
	v_and_b32_e32 v39, 0xffff0000, v104
	v_lshlrev_b32_e32 v26, 16, v101
	v_and_b32_e32 v29, 0xffff0000, v101
	v_lshlrev_b32_e32 v14, 16, v105
	v_and_b32_e32 v15, 0xffff0000, v105
	v_lshlrev_b32_e32 v18, 16, v106
	v_and_b32_e32 v19, 0xffff0000, v106
	v_mul_f32_e32 v9, 0x3fb8aa3b, v9
	v_mul_f32_e32 v20, 0x3fb8aa3b, v40
	v_and_b32_e32 v35, 0xffff0000, v99
	v_lshlrev_b32_e32 v36, 16, v99
	v_lshlrev_b32_e32 v30, 16, v102
	v_and_b32_e32 v13, 0xffff0000, v102
	v_lshlrev_b32_e32 v34, 16, v103
	v_and_b32_e32 v37, 0xffff0000, v103
	v_lshlrev_b32_e32 v16, 16, v107
	v_and_b32_e32 v17, 0xffff0000, v107
	v_mul_f32_e32 v5, 0x3fb8aa3b, v5
	v_exp_f32_e32 v21, v9
	v_exp_f32_e32 v20, v20
	v_exp_f32_e32 v5, v5
	v_and_b32_e32 v25, 0xffff0000, v96
	v_lshlrev_b32_e32 v10, 16, v96
	v_add_f32_e32 v9, v21, v20
	v_add_f32_e32 v9, v5, v9
	v_and_b32_e32 v31, 0xffff0000, v98
	v_rcp_f32_e32 v40, v9
	s_nop 0
	v_lshlrev_b32_e32 v12, 16, v98
	v_pk_mul_f32 v[20:21], v[20:21], v[40:41] op_sel_hi:[1,0]
	v_mul_f32_e32 v42, v5, v40
	v_pk_mul_f32 v[10:11], v[20:21], v[10:11] op_sel:[1,0] op_sel_hi:[0,1]
	v_pk_mul_f32 v[28:29], v[20:21], v[28:29] op_sel:[1,0] op_sel_hi:[0,1]
	v_pk_mul_f32 v[12:13], v[20:21], v[12:13] op_sel:[1,0] op_sel_hi:[0,1]
	v_pk_mul_f32 v[36:37], v[20:21], v[36:37] op_sel:[1,0] op_sel_hi:[0,1]
	v_pk_fma_f32 v[10:11], v[20:21], v[24:25], v[10:11]
	v_pk_fma_f32 v[24:25], v[20:21], v[26:27], v[28:29]
	v_pk_fma_f32 v[12:13], v[20:21], v[30:31], v[12:13]
	v_pk_fma_f32 v[20:21], v[20:21], v[34:35], v[36:37]
	v_pk_fma_f32 v[10:11], v[42:43], v[38:39], v[10:11] op_sel_hi:[0,1,1]
	v_pk_fma_f32 v[14:15], v[42:43], v[14:15], v[24:25] op_sel_hi:[0,1,1]
	v_pk_fma_f32 v[12:13], v[42:43], v[18:19], v[12:13] op_sel_hi:[0,1,1]
	v_pk_fma_f32 v[16:17], v[42:43], v[16:17], v[20:21] op_sel_hi:[0,1,1]
	v_cvt_pk_bf16_f32 v10, v10, v11
	v_cvt_pk_bf16_f32 v11, v14, v15
	v_cvt_pk_bf16_f32 v12, v12, v13
	v_cvt_pk_bf16_f32 v13, v16, v17
	v_add_u32_e32 v8, 0x30000, v7
	global_store_dwordx4 v8, v[10:13], s[8:9] offset:1024
	s_waitcnt vmcnt(22)
	v_max3_f32 v5, v140, v141, v142
	v_sub_f32_e32 v9, v140, v5
	v_sub_f32_e32 v40, v141, v5
	v_and_b32_e32 v27, 0xffff0000, v129
	v_lshlrev_b32_e32 v28, 16, v129
	v_sub_f32_e32 v5, v142, v5
	v_lshlrev_b32_e32 v24, 16, v132
	v_and_b32_e32 v11, 0xffff0000, v132
	v_lshlrev_b32_e32 v38, 16, v136
	v_and_b32_e32 v39, 0xffff0000, v136
	v_lshlrev_b32_e32 v26, 16, v133
	v_and_b32_e32 v29, 0xffff0000, v133
	v_lshlrev_b32_e32 v14, 16, v137
	v_and_b32_e32 v15, 0xffff0000, v137
	v_lshlrev_b32_e32 v18, 16, v138
	v_and_b32_e32 v19, 0xffff0000, v138
	v_mul_f32_e32 v9, 0x3fb8aa3b, v9
	v_mul_f32_e32 v20, 0x3fb8aa3b, v40
	v_and_b32_e32 v35, 0xffff0000, v131
	v_lshlrev_b32_e32 v36, 16, v131
	v_lshlrev_b32_e32 v30, 16, v134
	v_and_b32_e32 v13, 0xffff0000, v134
	v_lshlrev_b32_e32 v34, 16, v135
	v_and_b32_e32 v37, 0xffff0000, v135
	v_lshlrev_b32_e32 v16, 16, v139
	v_and_b32_e32 v17, 0xffff0000, v139
	v_mul_f32_e32 v5, 0x3fb8aa3b, v5
	v_exp_f32_e32 v21, v9
	v_exp_f32_e32 v20, v20
	v_exp_f32_e32 v5, v5
	v_and_b32_e32 v25, 0xffff0000, v128
	v_lshlrev_b32_e32 v10, 16, v128
	v_add_f32_e32 v9, v21, v20
	v_add_f32_e32 v9, v5, v9
	v_and_b32_e32 v31, 0xffff0000, v130
	v_rcp_f32_e32 v40, v9
	s_nop 0
	v_lshlrev_b32_e32 v12, 16, v130
	v_pk_mul_f32 v[20:21], v[20:21], v[40:41] op_sel_hi:[1,0]
	v_mul_f32_e32 v42, v5, v40
	v_pk_mul_f32 v[10:11], v[20:21], v[10:11] op_sel:[1,0] op_sel_hi:[0,1]
	v_pk_mul_f32 v[28:29], v[20:21], v[28:29] op_sel:[1,0] op_sel_hi:[0,1]
	v_pk_mul_f32 v[12:13], v[20:21], v[12:13] op_sel:[1,0] op_sel_hi:[0,1]
	v_pk_mul_f32 v[36:37], v[20:21], v[36:37] op_sel:[1,0] op_sel_hi:[0,1]
	v_pk_fma_f32 v[10:11], v[20:21], v[24:25], v[10:11]
	v_pk_fma_f32 v[24:25], v[20:21], v[26:27], v[28:29]
	v_pk_fma_f32 v[12:13], v[20:21], v[30:31], v[12:13]
	v_pk_fma_f32 v[20:21], v[20:21], v[34:35], v[36:37]
	v_pk_fma_f32 v[10:11], v[42:43], v[38:39], v[10:11] op_sel_hi:[0,1,1]
	v_pk_fma_f32 v[14:15], v[42:43], v[14:15], v[24:25] op_sel_hi:[0,1,1]
	v_pk_fma_f32 v[12:13], v[42:43], v[18:19], v[12:13] op_sel_hi:[0,1,1]
	v_pk_fma_f32 v[16:17], v[42:43], v[16:17], v[20:21] op_sel_hi:[0,1,1]
	v_cvt_pk_bf16_f32 v10, v10, v11
	v_cvt_pk_bf16_f32 v11, v14, v15
	v_cvt_pk_bf16_f32 v12, v12, v13
	v_cvt_pk_bf16_f32 v13, v16, v17
	v_add_u32_e32 v8, 0x40000, v7
	global_store_dwordx4 v8, v[10:13], s[8:9] offset:1024
	s_waitcnt vmcnt(17)
	v_max3_f32 v5, v164, v165, v166
	v_sub_f32_e32 v9, v164, v5
	v_sub_f32_e32 v40, v165, v5
	v_and_b32_e32 v27, 0xffff0000, v153
	v_lshlrev_b32_e32 v28, 16, v153
	v_sub_f32_e32 v5, v166, v5
	v_lshlrev_b32_e32 v24, 16, v156
	v_and_b32_e32 v11, 0xffff0000, v156
	v_lshlrev_b32_e32 v38, 16, v160
	v_and_b32_e32 v39, 0xffff0000, v160
	v_lshlrev_b32_e32 v26, 16, v157
	v_and_b32_e32 v29, 0xffff0000, v157
	v_lshlrev_b32_e32 v14, 16, v161
	v_and_b32_e32 v15, 0xffff0000, v161
	v_lshlrev_b32_e32 v18, 16, v162
	v_and_b32_e32 v19, 0xffff0000, v162
	v_mul_f32_e32 v9, 0x3fb8aa3b, v9
	v_mul_f32_e32 v20, 0x3fb8aa3b, v40
	v_and_b32_e32 v35, 0xffff0000, v155
	v_lshlrev_b32_e32 v36, 16, v155
	v_lshlrev_b32_e32 v30, 16, v158
	v_and_b32_e32 v13, 0xffff0000, v158
	v_lshlrev_b32_e32 v34, 16, v159
	v_and_b32_e32 v37, 0xffff0000, v159
	v_lshlrev_b32_e32 v16, 16, v163
	v_and_b32_e32 v17, 0xffff0000, v163
	v_mul_f32_e32 v5, 0x3fb8aa3b, v5
	v_exp_f32_e32 v21, v9
	v_exp_f32_e32 v20, v20
	v_exp_f32_e32 v5, v5
	v_and_b32_e32 v25, 0xffff0000, v152
	v_lshlrev_b32_e32 v10, 16, v152
	v_add_f32_e32 v9, v21, v20
	v_add_f32_e32 v9, v5, v9
	v_and_b32_e32 v31, 0xffff0000, v154
	v_rcp_f32_e32 v40, v9
	s_nop 0
	v_lshlrev_b32_e32 v12, 16, v154
	v_pk_mul_f32 v[20:21], v[20:21], v[40:41] op_sel_hi:[1,0]
	v_mul_f32_e32 v42, v5, v40
	v_pk_mul_f32 v[10:11], v[20:21], v[10:11] op_sel:[1,0] op_sel_hi:[0,1]
	v_pk_mul_f32 v[28:29], v[20:21], v[28:29] op_sel:[1,0] op_sel_hi:[0,1]
	v_pk_mul_f32 v[12:13], v[20:21], v[12:13] op_sel:[1,0] op_sel_hi:[0,1]
	v_pk_mul_f32 v[36:37], v[20:21], v[36:37] op_sel:[1,0] op_sel_hi:[0,1]
	v_pk_fma_f32 v[10:11], v[20:21], v[24:25], v[10:11]
	v_pk_fma_f32 v[24:25], v[20:21], v[26:27], v[28:29]
	v_pk_fma_f32 v[12:13], v[20:21], v[30:31], v[12:13]
	v_pk_fma_f32 v[20:21], v[20:21], v[34:35], v[36:37]
	v_pk_fma_f32 v[10:11], v[42:43], v[38:39], v[10:11] op_sel_hi:[0,1,1]
	v_pk_fma_f32 v[14:15], v[42:43], v[14:15], v[24:25] op_sel_hi:[0,1,1]
	v_pk_fma_f32 v[12:13], v[42:43], v[18:19], v[12:13] op_sel_hi:[0,1,1]
	v_pk_fma_f32 v[16:17], v[42:43], v[16:17], v[20:21] op_sel_hi:[0,1,1]
	v_cvt_pk_bf16_f32 v10, v10, v11
	v_cvt_pk_bf16_f32 v11, v14, v15
	v_cvt_pk_bf16_f32 v12, v12, v13
	v_cvt_pk_bf16_f32 v13, v16, v17
	v_add_u32_e32 v8, 0x50000, v7
	global_store_dwordx4 v8, v[10:13], s[8:9] offset:1024
	s_waitcnt vmcnt(12)
	v_max3_f32 v5, v218, v219, v220
	v_sub_f32_e32 v9, v218, v5
	v_sub_f32_e32 v40, v219, v5
	v_and_b32_e32 v27, 0xffff0000, v207
	v_lshlrev_b32_e32 v28, 16, v207
	v_sub_f32_e32 v5, v220, v5
	v_lshlrev_b32_e32 v24, 16, v210
	v_and_b32_e32 v11, 0xffff0000, v210
	v_lshlrev_b32_e32 v38, 16, v214
	v_and_b32_e32 v39, 0xffff0000, v214
	v_lshlrev_b32_e32 v26, 16, v211
	v_and_b32_e32 v29, 0xffff0000, v211
	v_lshlrev_b32_e32 v14, 16, v215
	v_and_b32_e32 v15, 0xffff0000, v215
	v_lshlrev_b32_e32 v18, 16, v216
	v_and_b32_e32 v19, 0xffff0000, v216
	v_mul_f32_e32 v9, 0x3fb8aa3b, v9
	v_mul_f32_e32 v20, 0x3fb8aa3b, v40
	v_and_b32_e32 v35, 0xffff0000, v209
	v_lshlrev_b32_e32 v36, 16, v209
	v_lshlrev_b32_e32 v30, 16, v212
	v_and_b32_e32 v13, 0xffff0000, v212
	v_lshlrev_b32_e32 v34, 16, v213
	v_and_b32_e32 v37, 0xffff0000, v213
	v_lshlrev_b32_e32 v16, 16, v217
	v_and_b32_e32 v17, 0xffff0000, v217
	v_mul_f32_e32 v5, 0x3fb8aa3b, v5
	v_exp_f32_e32 v21, v9
	v_exp_f32_e32 v20, v20
	v_exp_f32_e32 v5, v5
	v_and_b32_e32 v25, 0xffff0000, v206
	v_lshlrev_b32_e32 v10, 16, v206
	v_add_f32_e32 v9, v21, v20
	v_add_f32_e32 v9, v5, v9
	v_and_b32_e32 v31, 0xffff0000, v208
	v_rcp_f32_e32 v40, v9
	s_nop 0
	v_lshlrev_b32_e32 v12, 16, v208
	v_pk_mul_f32 v[20:21], v[20:21], v[40:41] op_sel_hi:[1,0]
	v_mul_f32_e32 v42, v5, v40
	v_pk_mul_f32 v[10:11], v[20:21], v[10:11] op_sel:[1,0] op_sel_hi:[0,1]
	v_pk_mul_f32 v[28:29], v[20:21], v[28:29] op_sel:[1,0] op_sel_hi:[0,1]
	v_pk_mul_f32 v[12:13], v[20:21], v[12:13] op_sel:[1,0] op_sel_hi:[0,1]
	v_pk_mul_f32 v[36:37], v[20:21], v[36:37] op_sel:[1,0] op_sel_hi:[0,1]
	v_pk_fma_f32 v[10:11], v[20:21], v[24:25], v[10:11]
	v_pk_fma_f32 v[24:25], v[20:21], v[26:27], v[28:29]
	v_pk_fma_f32 v[12:13], v[20:21], v[30:31], v[12:13]
	v_pk_fma_f32 v[20:21], v[20:21], v[34:35], v[36:37]
	v_pk_fma_f32 v[10:11], v[42:43], v[38:39], v[10:11] op_sel_hi:[0,1,1]
	v_pk_fma_f32 v[14:15], v[42:43], v[14:15], v[24:25] op_sel_hi:[0,1,1]
	v_pk_fma_f32 v[12:13], v[42:43], v[18:19], v[12:13] op_sel_hi:[0,1,1]
	v_pk_fma_f32 v[16:17], v[42:43], v[16:17], v[20:21] op_sel_hi:[0,1,1]
	v_cvt_pk_bf16_f32 v10, v10, v11
	v_cvt_pk_bf16_f32 v11, v14, v15
	v_cvt_pk_bf16_f32 v12, v12, v13
	v_cvt_pk_bf16_f32 v13, v16, v17
	v_add_u32_e32 v8, 0x60000, v7
	global_store_dwordx4 v8, v[10:13], s[8:9] offset:1024
	s_waitcnt vmcnt(7)
	v_max3_f32 v5, v244, v245, v246
	v_sub_f32_e32 v9, v244, v5
	v_sub_f32_e32 v40, v245, v5
	v_and_b32_e32 v27, 0xffff0000, v233
	v_lshlrev_b32_e32 v28, 16, v233
	v_sub_f32_e32 v5, v246, v5
	v_lshlrev_b32_e32 v24, 16, v236
	v_and_b32_e32 v11, 0xffff0000, v236
	v_lshlrev_b32_e32 v38, 16, v240
	v_and_b32_e32 v39, 0xffff0000, v240
	v_lshlrev_b32_e32 v26, 16, v237
	v_and_b32_e32 v29, 0xffff0000, v237
	v_lshlrev_b32_e32 v14, 16, v241
	v_and_b32_e32 v15, 0xffff0000, v241
	v_lshlrev_b32_e32 v18, 16, v242
	v_and_b32_e32 v19, 0xffff0000, v242
	v_mul_f32_e32 v9, 0x3fb8aa3b, v9
	v_mul_f32_e32 v20, 0x3fb8aa3b, v40
	v_and_b32_e32 v35, 0xffff0000, v235
	v_lshlrev_b32_e32 v36, 16, v235
	v_lshlrev_b32_e32 v30, 16, v238
	v_and_b32_e32 v13, 0xffff0000, v238
	v_lshlrev_b32_e32 v34, 16, v239
	v_and_b32_e32 v37, 0xffff0000, v239
	v_lshlrev_b32_e32 v16, 16, v243
	v_and_b32_e32 v17, 0xffff0000, v243
	v_mul_f32_e32 v5, 0x3fb8aa3b, v5
	v_exp_f32_e32 v21, v9
	v_exp_f32_e32 v20, v20
	v_exp_f32_e32 v5, v5
	v_and_b32_e32 v25, 0xffff0000, v232
	v_lshlrev_b32_e32 v10, 16, v232
	v_add_f32_e32 v9, v21, v20
	v_add_f32_e32 v9, v5, v9
	v_and_b32_e32 v31, 0xffff0000, v234
	v_rcp_f32_e32 v40, v9
	s_nop 0
	v_lshlrev_b32_e32 v12, 16, v234
	v_pk_mul_f32 v[20:21], v[20:21], v[40:41] op_sel_hi:[1,0]
	v_mul_f32_e32 v42, v5, v40
	v_pk_mul_f32 v[10:11], v[20:21], v[10:11] op_sel:[1,0] op_sel_hi:[0,1]
	v_pk_mul_f32 v[28:29], v[20:21], v[28:29] op_sel:[1,0] op_sel_hi:[0,1]
	v_pk_mul_f32 v[12:13], v[20:21], v[12:13] op_sel:[1,0] op_sel_hi:[0,1]
	v_pk_mul_f32 v[36:37], v[20:21], v[36:37] op_sel:[1,0] op_sel_hi:[0,1]
	v_pk_fma_f32 v[10:11], v[20:21], v[24:25], v[10:11]
	v_pk_fma_f32 v[24:25], v[20:21], v[26:27], v[28:29]
	v_pk_fma_f32 v[12:13], v[20:21], v[30:31], v[12:13]
	v_pk_fma_f32 v[20:21], v[20:21], v[34:35], v[36:37]
	v_pk_fma_f32 v[10:11], v[42:43], v[38:39], v[10:11] op_sel_hi:[0,1,1]
	v_pk_fma_f32 v[14:15], v[42:43], v[14:15], v[24:25] op_sel_hi:[0,1,1]
	v_pk_fma_f32 v[12:13], v[42:43], v[18:19], v[12:13] op_sel_hi:[0,1,1]
	v_pk_fma_f32 v[16:17], v[42:43], v[16:17], v[20:21] op_sel_hi:[0,1,1]
	v_cvt_pk_bf16_f32 v10, v10, v11
	v_cvt_pk_bf16_f32 v11, v14, v15
	v_cvt_pk_bf16_f32 v12, v12, v13
	v_cvt_pk_bf16_f32 v13, v16, v17
	v_add_u32_e32 v8, 0x70000, v7
	global_store_dwordx4 v8, v[10:13], s[8:9] offset:1024
	s_setprio 0
	s_waitcnt vmcnt(0)
	s_barrier
	s_mov_b64 s[0:1], exec
	v_readlane_b32 s2, v254, 29
	v_readlane_b32 s3, v254, 30
	s_and_b64 s[2:3], s[0:1], s[2:3]
	s_mov_b64 exec, s[2:3]
	s_cbranch_execz .LBB0_605
	s_andn2_b64 vcc, exec, s[42:43]
	s_cbranch_vccnz .LBB0_594
	buffer_wbl2 sc1
	s_waitcnt vmcnt(0)
	s_waitcnt vmcnt(0)

.Lskew_done_p5:
	s_cmp_lt_u32 s89, 4
	s_cbranch_scc1 .Lap_p5
	s_setprio 1

.LBB0_936:
	s_setprio 0
	s_waitcnt vmcnt(0)
	v_cndmask_b32_e64 v0, 0, 1, s[42:43]
	v_cmp_ne_u32_e64 s[2:3], 1, v0
	s_barrier
	s_mov_b64 s[0:1], exec
	v_readlane_b32 s4, v254, 29
	v_readlane_b32 s5, v254, 30
	s_and_b64 s[4:5], s[0:1], s[4:5]
	s_mov_b64 exec, s[4:5]
	s_cbranch_execz .LBB0_950
	s_and_b64 vcc, exec, s[2:3]
	s_cbranch_vccnz .LBB0_939
	buffer_wbl2 sc1
	s_waitcnt vmcnt(0)
	s_waitcnt vmcnt(0)
